# norm: adaLN shift/scale loads hoisted; EpiRes: residual loads batched (15+1) with saddr addressing
# speedup vs baseline: 1.0240x; 1.0150x over previous
; __device__ __forceinline__ unsigned pk2(float lo, float hi) { const f32x2_t v = {lo, hi}; const bf16v2_t b = __builtin_convertvector(v, bf16v2_t); return __builtin_bit_cast(unsigned, b); }
; __device__ __forceinline__ float bflo(unsigned u) { return __uint_as_float(u << 16); }
; __device__ __forceinline__ float bfhi(unsigned u) { return __uint_as_float(u & 0xffff0000u); }
;     __device__ __forceinline__ void operator()(const AccT& acc, const pg8::Unit& u, int wr, int wc, int fr_, int fq_) const {
;     ...
; #pragma unroll
;         for (int ai = 0; ai < 2; ++ai)
; #pragma unroll
;             for (int m = 0; m < 4; ++m) {
;                 bf16_t* rowp = R + (size_t)(row0 + ai * 128 + m * 16) * D + col0;
; #pragma unroll
;                 for (int bj = 0; bj < 2; ++bj) {
;                     const u32x4 rv = *(const u32x4*)(rowp + bj * 128);
;                     f32x4 r0, r1; r0[0] = bflo(rv[0]); r0[1] = bfhi(rv[0]); r0[2] = bflo(rv[1]); r0[3] = bfhi(rv[1]); r1[0] = bflo(rv[2]); r1[1] = bfhi(rv[2]); r1[2] = bflo(rv[3]); r1[3] = bfhi(rv[3]);
;                     r0 += gv[bj][0] * acc[ai][bj][m][0]; r1 += gv[bj][1] * acc[ai][bj][m][1];
;                     u32x4 o; o[0] = pk2(r0[0], r0[1]); o[1] = pk2(r0[2], r0[3]); o[2] = pk2(r1[0], r1[1]); o[3] = pk2(r1[2], r1[3]);
;                     *(u32x4*)(rowp + bj * 128) = o;
;                 }
;             }
.LBB0_417:
	v_lshlrev_b32_e32 v169, 11, v166
	v_lshl_add_u32 v168, v164, 1, v169
	global_load_dwordx4 v[192:195], v168, s[40:41]
	global_load_dwordx4 v[196:199], v168, s[40:41] offset:256
	s_add_u32 s98, s40, 0x8000
	s_addc_u32 s99, s41, 0
	global_load_dwordx4 v[200:203], v168, s[98:99]
	global_load_dwordx4 v[204:207], v168, s[98:99] offset:256
	s_add_u32 s100, s40, 0x10000
	s_addc_u32 s101, s41, 0
	global_load_dwordx4 v[208:211], v168, s[100:101]
	global_load_dwordx4 v[212:215], v168, s[100:101] offset:256
	s_add_u32 s98, s40, 0x18000
	s_addc_u32 s99, s41, 0
	global_load_dwordx4 v[216:219], v168, s[98:99]
	global_load_dwordx4 v[220:223], v168, s[98:99] offset:256
	s_add_u32 s100, s40, 0x40000
	s_addc_u32 s101, s41, 0
	global_load_dwordx4 v[224:227], v168, s[100:101]
	global_load_dwordx4 v[228:231], v168, s[100:101] offset:256
	s_add_u32 s98, s40, 0x48000
	s_addc_u32 s99, s41, 0
	global_load_dwordx4 v[232:235], v168, s[98:99]
	global_load_dwordx4 v[236:239], v168, s[98:99] offset:256
	s_add_u32 s100, s40, 0x50000
	s_addc_u32 s101, s41, 0
	global_load_dwordx4 v[240:243], v168, s[100:101]
	global_load_dwordx4 v[244:247], v168, s[100:101] offset:256
	s_add_u32 s98, s40, 0x58000
	s_addc_u32 s99, s41, 0
	global_load_dwordx4 v[248:251], v168, s[98:99]
	s_waitcnt vmcnt(14)
	v_lshlrev_b32_e32 v164, 16, v192
	v_and_b32_e32 v165, 0xffff0000, v192
	v_lshlrev_b32_e32 v192, 16, v193
	v_and_b32_e32 v193, 0xffff0000, v193
	v_lshlrev_b32_e32 v166, 16, v194
	v_and_b32_e32 v167, 0xffff0000, v194
	v_lshlrev_b32_e32 v194, 16, v195
	v_and_b32_e32 v195, 0xffff0000, v195
	v_pk_fma_f32 v[128:129], v[128:129], v[158:159], v[192:193]
	v_pk_fma_f32 v[126:127], v[126:127], v[162:163], v[164:165]
	v_pk_fma_f32 v[124:125], v[124:125], v[156:157], v[194:195]
	v_pk_fma_f32 v[122:123], v[122:123], v[160:161], v[166:167]
	v_cvt_pk_bf16_f32 v126, v126, v127
	v_cvt_pk_bf16_f32 v127, v128, v129
	v_cvt_pk_bf16_f32 v128, v122, v123
	v_cvt_pk_bf16_f32 v129, v124, v125
	global_store_dwordx4 v168, v[126:129], s[40:41]
	s_add_u32 s100, s40, 0x58000
	s_addc_u32 s101, s41, 0
	global_load_dwordx4 v[192:195], v168, s[100:101] offset:256
	s_waitcnt vmcnt(15)
	v_lshlrev_b32_e32 v164, 16, v196
	v_and_b32_e32 v165, 0xffff0000, v196
	v_lshlrev_b32_e32 v196, 16, v197
	v_and_b32_e32 v197, 0xffff0000, v197
	v_lshlrev_b32_e32 v166, 16, v198
	v_and_b32_e32 v167, 0xffff0000, v198
	v_lshlrev_b32_e32 v198, 16, v199
	v_and_b32_e32 v199, 0xffff0000, v199
	v_pk_fma_f32 v[120:121], v[120:121], v[154:155], v[196:197]
	v_pk_fma_f32 v[118:119], v[118:119], v[152:153], v[164:165]
	v_pk_fma_f32 v[116:117], v[116:117], v[150:151], v[198:199]
	v_pk_fma_f32 v[114:115], v[114:115], v[148:149], v[166:167]
	v_cvt_pk_bf16_f32 v118, v118, v119
	v_cvt_pk_bf16_f32 v119, v120, v121
	v_cvt_pk_bf16_f32 v120, v114, v115
	v_cvt_pk_bf16_f32 v121, v116, v117
	global_store_dwordx4 v168, v[118:121], s[40:41] offset:256
	s_waitcnt vmcnt(15)
	v_lshlrev_b32_e32 v164, 16, v200
	v_and_b32_e32 v165, 0xffff0000, v200
	v_lshlrev_b32_e32 v200, 16, v201
	v_and_b32_e32 v201, 0xffff0000, v201
	v_lshlrev_b32_e32 v166, 16, v202
	v_and_b32_e32 v167, 0xffff0000, v202
	v_lshlrev_b32_e32 v202, 16, v203
	v_and_b32_e32 v203, 0xffff0000, v203
	v_pk_fma_f32 v[112:113], v[112:113], v[158:159], v[200:201]
	v_pk_fma_f32 v[110:111], v[110:111], v[162:163], v[164:165]
	v_pk_fma_f32 v[108:109], v[108:109], v[156:157], v[202:203]
	v_pk_fma_f32 v[106:107], v[106:107], v[160:161], v[166:167]
	v_cvt_pk_bf16_f32 v110, v110, v111
	v_cvt_pk_bf16_f32 v111, v112, v113
	v_cvt_pk_bf16_f32 v112, v106, v107
	v_cvt_pk_bf16_f32 v113, v108, v109
	s_add_u32 s98, s40, 0x8000
	s_addc_u32 s99, s41, 0
	global_store_dwordx4 v168, v[110:113], s[98:99]
	s_waitcnt vmcnt(15)
	v_lshlrev_b32_e32 v164, 16, v204
	v_and_b32_e32 v165, 0xffff0000, v204
	v_lshlrev_b32_e32 v204, 16, v205
	v_and_b32_e32 v205, 0xffff0000, v205
	v_lshlrev_b32_e32 v166, 16, v206
	v_and_b32_e32 v167, 0xffff0000, v206
	v_lshlrev_b32_e32 v206, 16, v207
	v_and_b32_e32 v207, 0xffff0000, v207
	v_pk_fma_f32 v[104:105], v[104:105], v[154:155], v[204:205]
	v_pk_fma_f32 v[102:103], v[102:103], v[152:153], v[164:165]
	v_pk_fma_f32 v[100:101], v[100:101], v[150:151], v[206:207]
	v_pk_fma_f32 v[98:99], v[98:99], v[148:149], v[166:167]
	v_cvt_pk_bf16_f32 v102, v102, v103
	v_cvt_pk_bf16_f32 v103, v104, v105
	v_cvt_pk_bf16_f32 v104, v98, v99
	v_cvt_pk_bf16_f32 v105, v100, v101
	global_store_dwordx4 v168, v[102:105], s[98:99] offset:256
	s_waitcnt vmcnt(15)
	v_lshlrev_b32_e32 v164, 16, v208
	v_and_b32_e32 v165, 0xffff0000, v208
	v_lshlrev_b32_e32 v208, 16, v209
	v_and_b32_e32 v209, 0xffff0000, v209
	v_lshlrev_b32_e32 v166, 16, v210
	v_and_b32_e32 v167, 0xffff0000, v210
	v_lshlrev_b32_e32 v210, 16, v211
	v_and_b32_e32 v211, 0xffff0000, v211
	v_pk_fma_f32 v[96:97], v[96:97], v[158:159], v[208:209]
	v_pk_fma_f32 v[94:95], v[94:95], v[162:163], v[164:165]
	v_pk_fma_f32 v[92:93], v[92:93], v[156:157], v[210:211]
	v_pk_fma_f32 v[90:91], v[90:91], v[160:161], v[166:167]
	v_cvt_pk_bf16_f32 v94, v94, v95
	v_cvt_pk_bf16_f32 v95, v96, v97
	v_cvt_pk_bf16_f32 v96, v90, v91
	v_cvt_pk_bf16_f32 v97, v92, v93
	s_add_u32 s100, s40, 0x10000
	s_addc_u32 s101, s41, 0
	global_store_dwordx4 v168, v[94:97], s[100:101]
	s_waitcnt vmcnt(15)
	v_lshlrev_b32_e32 v164, 16, v212
	v_and_b32_e32 v165, 0xffff0000, v212
	v_lshlrev_b32_e32 v212, 16, v213
	v_and_b32_e32 v213, 0xffff0000, v213
	v_lshlrev_b32_e32 v166, 16, v214
	v_and_b32_e32 v167, 0xffff0000, v214
	v_lshlrev_b32_e32 v214, 16, v215
	v_and_b32_e32 v215, 0xffff0000, v215
	v_pk_fma_f32 v[88:89], v[88:89], v[154:155], v[212:213]
	v_pk_fma_f32 v[86:87], v[86:87], v[152:153], v[164:165]
	v_pk_fma_f32 v[84:85], v[84:85], v[150:151], v[214:215]
	v_pk_fma_f32 v[82:83], v[82:83], v[148:149], v[166:167]
	v_cvt_pk_bf16_f32 v86, v86, v87
	v_cvt_pk_bf16_f32 v87, v88, v89
	v_cvt_pk_bf16_f32 v88, v82, v83
	v_cvt_pk_bf16_f32 v89, v84, v85
	global_store_dwordx4 v168, v[86:89], s[100:101] offset:256
	s_waitcnt vmcnt(15)
; __device__ __forceinline__ unsigned pk2(float lo, float hi) { const f32x2_t v = {lo, hi}; const bf16v2_t b = __builtin_convertvector(v, bf16v2_t); return __builtin_bit_cast(unsigned, b); }
; __device__ __forceinline__ float bflo(unsigned u) { return __uint_as_float(u << 16); }
; __device__ __forceinline__ float bfhi(unsigned u) { return __uint_as_float(u & 0xffff0000u); }
;     __device__ __forceinline__ void operator()(const AccT& acc, const pg8::Unit& u, int wr, int wc, int fr_, int fq_) const {
;     ...
; #pragma unroll
;         for (int ai = 0; ai < 2; ++ai)
; #pragma unroll
;             for (int m = 0; m < 4; ++m) {
;                 bf16_t* rowp = R + (size_t)(row0 + ai * 128 + m * 16) * D + col0;
; #pragma unroll
;                 for (int bj = 0; bj < 2; ++bj) {
;                     const u32x4 rv = *(const u32x4*)(rowp + bj * 128);
;                     f32x4 r0, r1; r0[0] = bflo(rv[0]); r0[1] = bfhi(rv[0]); r0[2] = bflo(rv[1]); r0[3] = bfhi(rv[1]); r1[0] = bflo(rv[2]); r1[1] = bfhi(rv[2]); r1[2] = bflo(rv[3]); r1[3] = bfhi(rv[3]);
;                     r0 += gv[bj][0] * acc[ai][bj][m][0]; r1 += gv[bj][1] * acc[ai][bj][m][1];
;                     u32x4 o; o[0] = pk2(r0[0], r0[1]); o[1] = pk2(r0[2], r0[3]); o[2] = pk2(r1[0], r1[1]); o[3] = pk2(r1[2], r1[3]);
;                     *(u32x4*)(rowp + bj * 128) = o;
;                 }
;             }
	v_lshlrev_b32_e32 v164, 16, v216
	v_and_b32_e32 v165, 0xffff0000, v216
	v_lshlrev_b32_e32 v216, 16, v217
	v_and_b32_e32 v217, 0xffff0000, v217
	v_lshlrev_b32_e32 v166, 16, v218
	v_and_b32_e32 v167, 0xffff0000, v218
	v_lshlrev_b32_e32 v218, 16, v219
	v_and_b32_e32 v219, 0xffff0000, v219
	v_pk_fma_f32 v[80:81], v[80:81], v[158:159], v[216:217]
	v_pk_fma_f32 v[78:79], v[78:79], v[162:163], v[164:165]
	v_pk_fma_f32 v[76:77], v[76:77], v[156:157], v[218:219]
	v_pk_fma_f32 v[74:75], v[74:75], v[160:161], v[166:167]
	v_cvt_pk_bf16_f32 v78, v78, v79
	v_cvt_pk_bf16_f32 v79, v80, v81
	v_cvt_pk_bf16_f32 v80, v74, v75
	v_cvt_pk_bf16_f32 v81, v76, v77
	s_add_u32 s98, s40, 0x18000
	s_addc_u32 s99, s41, 0
	global_store_dwordx4 v168, v[78:81], s[98:99]
	s_waitcnt vmcnt(15)
	v_lshlrev_b32_e32 v164, 16, v220
	v_and_b32_e32 v165, 0xffff0000, v220
	v_lshlrev_b32_e32 v220, 16, v221
	v_and_b32_e32 v221, 0xffff0000, v221
	v_lshlrev_b32_e32 v166, 16, v222
	v_and_b32_e32 v167, 0xffff0000, v222
	v_lshlrev_b32_e32 v222, 16, v223
	v_and_b32_e32 v223, 0xffff0000, v223
	v_pk_fma_f32 v[72:73], v[72:73], v[154:155], v[220:221]
	v_pk_fma_f32 v[70:71], v[70:71], v[152:153], v[164:165]
	v_pk_fma_f32 v[68:69], v[68:69], v[150:151], v[222:223]
	v_pk_fma_f32 v[66:67], v[66:67], v[148:149], v[166:167]
	v_cvt_pk_bf16_f32 v70, v70, v71
	v_cvt_pk_bf16_f32 v71, v72, v73
	v_cvt_pk_bf16_f32 v72, v66, v67
	v_cvt_pk_bf16_f32 v73, v68, v69
	global_store_dwordx4 v168, v[70:73], s[98:99] offset:256
	s_waitcnt vmcnt(15)
	v_lshlrev_b32_e32 v164, 16, v224
	v_and_b32_e32 v165, 0xffff0000, v224
	v_lshlrev_b32_e32 v224, 16, v225
	v_and_b32_e32 v225, 0xffff0000, v225
	v_lshlrev_b32_e32 v166, 16, v226
	v_and_b32_e32 v167, 0xffff0000, v226
	v_lshlrev_b32_e32 v226, 16, v227
	v_and_b32_e32 v227, 0xffff0000, v227
	v_pk_fma_f32 v[64:65], v[64:65], v[158:159], v[224:225]
	v_pk_fma_f32 v[62:63], v[62:63], v[162:163], v[164:165]
	v_pk_fma_f32 v[60:61], v[60:61], v[156:157], v[226:227]
	v_pk_fma_f32 v[58:59], v[58:59], v[160:161], v[166:167]
	v_cvt_pk_bf16_f32 v62, v62, v63
	v_cvt_pk_bf16_f32 v63, v64, v65
	v_cvt_pk_bf16_f32 v64, v58, v59
	v_cvt_pk_bf16_f32 v65, v60, v61
	s_add_u32 s100, s40, 0x40000
	s_addc_u32 s101, s41, 0
	global_store_dwordx4 v168, v[62:65], s[100:101]
	s_waitcnt vmcnt(15)
	v_lshlrev_b32_e32 v164, 16, v228
	v_and_b32_e32 v165, 0xffff0000, v228
	v_lshlrev_b32_e32 v228, 16, v229
	v_and_b32_e32 v229, 0xffff0000, v229
	v_lshlrev_b32_e32 v166, 16, v230
	v_and_b32_e32 v167, 0xffff0000, v230
	v_lshlrev_b32_e32 v230, 16, v231
	v_and_b32_e32 v231, 0xffff0000, v231
	v_pk_fma_f32 v[56:57], v[56:57], v[154:155], v[228:229]
	v_pk_fma_f32 v[54:55], v[54:55], v[152:153], v[164:165]
	v_pk_fma_f32 v[52:53], v[52:53], v[150:151], v[230:231]
	v_pk_fma_f32 v[50:51], v[50:51], v[148:149], v[166:167]
	v_cvt_pk_bf16_f32 v54, v54, v55
	v_cvt_pk_bf16_f32 v55, v56, v57
	v_cvt_pk_bf16_f32 v56, v50, v51
	v_cvt_pk_bf16_f32 v57, v52, v53
	global_store_dwordx4 v168, v[54:57], s[100:101] offset:256
	s_waitcnt vmcnt(15)
	v_lshlrev_b32_e32 v164, 16, v232
	v_and_b32_e32 v165, 0xffff0000, v232
	v_lshlrev_b32_e32 v232, 16, v233
	v_and_b32_e32 v233, 0xffff0000, v233
	v_lshlrev_b32_e32 v166, 16, v234
	v_and_b32_e32 v167, 0xffff0000, v234
	v_lshlrev_b32_e32 v234, 16, v235
	v_and_b32_e32 v235, 0xffff0000, v235
	v_pk_fma_f32 v[48:49], v[48:49], v[158:159], v[232:233]
	v_pk_fma_f32 v[46:47], v[46:47], v[162:163], v[164:165]
	v_pk_fma_f32 v[44:45], v[44:45], v[156:157], v[234:235]
	v_pk_fma_f32 v[42:43], v[42:43], v[160:161], v[166:167]
	v_cvt_pk_bf16_f32 v46, v46, v47
	v_cvt_pk_bf16_f32 v47, v48, v49
	v_cvt_pk_bf16_f32 v48, v42, v43
	v_cvt_pk_bf16_f32 v49, v44, v45
	s_add_u32 s98, s40, 0x48000
	s_addc_u32 s99, s41, 0
	global_store_dwordx4 v168, v[46:49], s[98:99]
	s_waitcnt vmcnt(15)
; __device__ __forceinline__ unsigned pk2(float lo, float hi) { const f32x2_t v = {lo, hi}; const bf16v2_t b = __builtin_convertvector(v, bf16v2_t); return __builtin_bit_cast(unsigned, b); }
; __device__ __forceinline__ float bflo(unsigned u) { return __uint_as_float(u << 16); }
; __device__ __forceinline__ float bfhi(unsigned u) { return __uint_as_float(u & 0xffff0000u); }
;     __device__ __forceinline__ void operator()(const AccT& acc, const pg8::Unit& u, int wr, int wc, int fr_, int fq_) const {
;     ...
; #pragma unroll
;         for (int ai = 0; ai < 2; ++ai)
; #pragma unroll
;             for (int m = 0; m < 4; ++m) {
;                 bf16_t* rowp = R + (size_t)(row0 + ai * 128 + m * 16) * D + col0;
; #pragma unroll
;                 for (int bj = 0; bj < 2; ++bj) {
;                     const u32x4 rv = *(const u32x4*)(rowp + bj * 128);
;                     f32x4 r0, r1; r0[0] = bflo(rv[0]); r0[1] = bfhi(rv[0]); r0[2] = bflo(rv[1]); r0[3] = bfhi(rv[1]); r1[0] = bflo(rv[2]); r1[1] = bfhi(rv[2]); r1[2] = bflo(rv[3]); r1[3] = bfhi(rv[3]);
;                     r0 += gv[bj][0] * acc[ai][bj][m][0]; r1 += gv[bj][1] * acc[ai][bj][m][1];
;                     u32x4 o; o[0] = pk2(r0[0], r0[1]); o[1] = pk2(r0[2], r0[3]); o[2] = pk2(r1[0], r1[1]); o[3] = pk2(r1[2], r1[3]);
;                     *(u32x4*)(rowp + bj * 128) = o;
;                 }
;             }
	v_lshlrev_b32_e32 v164, 16, v236
	v_and_b32_e32 v165, 0xffff0000, v236
	v_lshlrev_b32_e32 v236, 16, v237
	v_and_b32_e32 v237, 0xffff0000, v237
	v_lshlrev_b32_e32 v166, 16, v238
	v_and_b32_e32 v167, 0xffff0000, v238
	v_lshlrev_b32_e32 v238, 16, v239
	v_and_b32_e32 v239, 0xffff0000, v239
	v_pk_fma_f32 v[40:41], v[40:41], v[154:155], v[236:237]
	v_pk_fma_f32 v[38:39], v[38:39], v[152:153], v[164:165]
	v_pk_fma_f32 v[36:37], v[36:37], v[150:151], v[238:239]
	v_pk_fma_f32 v[34:35], v[34:35], v[148:149], v[166:167]
	v_cvt_pk_bf16_f32 v38, v38, v39
	v_cvt_pk_bf16_f32 v39, v40, v41
	v_cvt_pk_bf16_f32 v40, v34, v35
	v_cvt_pk_bf16_f32 v41, v36, v37
	global_store_dwordx4 v168, v[38:41], s[98:99] offset:256
	s_waitcnt vmcnt(15)
	v_lshlrev_b32_e32 v164, 16, v240
	v_and_b32_e32 v165, 0xffff0000, v240
	v_lshlrev_b32_e32 v240, 16, v241
	v_and_b32_e32 v241, 0xffff0000, v241
	v_lshlrev_b32_e32 v166, 16, v242
	v_and_b32_e32 v167, 0xffff0000, v242
	v_lshlrev_b32_e32 v242, 16, v243
	v_and_b32_e32 v243, 0xffff0000, v243
	v_pk_fma_f32 v[32:33], v[32:33], v[158:159], v[240:241]
	v_pk_fma_f32 v[30:31], v[30:31], v[162:163], v[164:165]
	v_pk_fma_f32 v[28:29], v[28:29], v[156:157], v[242:243]
	v_pk_fma_f32 v[26:27], v[26:27], v[160:161], v[166:167]
	v_cvt_pk_bf16_f32 v30, v30, v31
	v_cvt_pk_bf16_f32 v31, v32, v33
	v_cvt_pk_bf16_f32 v32, v26, v27
	v_cvt_pk_bf16_f32 v33, v28, v29
	s_add_u32 s100, s40, 0x50000
	s_addc_u32 s101, s41, 0
	global_store_dwordx4 v168, v[30:33], s[100:101]
	s_waitcnt vmcnt(15)
	v_lshlrev_b32_e32 v164, 16, v244
	v_and_b32_e32 v165, 0xffff0000, v244
	v_lshlrev_b32_e32 v244, 16, v245
	v_and_b32_e32 v245, 0xffff0000, v245
	v_lshlrev_b32_e32 v166, 16, v246
	v_and_b32_e32 v167, 0xffff0000, v246
	v_lshlrev_b32_e32 v246, 16, v247
	v_and_b32_e32 v247, 0xffff0000, v247
	v_pk_fma_f32 v[24:25], v[24:25], v[154:155], v[244:245]
	v_pk_fma_f32 v[22:23], v[22:23], v[152:153], v[164:165]
	v_pk_fma_f32 v[20:21], v[20:21], v[150:151], v[246:247]
	v_pk_fma_f32 v[18:19], v[18:19], v[148:149], v[166:167]
	v_cvt_pk_bf16_f32 v22, v22, v23
	v_cvt_pk_bf16_f32 v23, v24, v25
	v_cvt_pk_bf16_f32 v24, v18, v19
	v_cvt_pk_bf16_f32 v25, v20, v21
	global_store_dwordx4 v168, v[22:25], s[100:101] offset:256
	s_waitcnt vmcnt(15)
	v_lshlrev_b32_e32 v164, 16, v248
	v_and_b32_e32 v165, 0xffff0000, v248
	v_lshlrev_b32_e32 v248, 16, v249
	v_and_b32_e32 v249, 0xffff0000, v249
	v_lshlrev_b32_e32 v166, 16, v250
	v_and_b32_e32 v167, 0xffff0000, v250
	v_lshlrev_b32_e32 v250, 16, v251
	v_and_b32_e32 v251, 0xffff0000, v251
	v_pk_fma_f32 v[16:17], v[16:17], v[158:159], v[248:249]
	v_pk_fma_f32 v[14:15], v[14:15], v[162:163], v[164:165]
	v_pk_fma_f32 v[12:13], v[12:13], v[156:157], v[250:251]
	v_pk_fma_f32 v[10:11], v[10:11], v[160:161], v[166:167]
	v_cvt_pk_bf16_f32 v14, v14, v15
	v_cvt_pk_bf16_f32 v15, v16, v17
	v_cvt_pk_bf16_f32 v16, v10, v11
	v_cvt_pk_bf16_f32 v17, v12, v13
	s_add_u32 s98, s40, 0x58000
	s_addc_u32 s99, s41, 0
	global_store_dwordx4 v168, v[14:17], s[98:99]
	s_waitcnt vmcnt(14)
	v_lshlrev_b32_e32 v164, 16, v192
	v_and_b32_e32 v165, 0xffff0000, v192
	v_lshlrev_b32_e32 v192, 16, v193
	v_and_b32_e32 v193, 0xffff0000, v193
	v_lshlrev_b32_e32 v166, 16, v194
	v_and_b32_e32 v167, 0xffff0000, v194
	v_lshlrev_b32_e32 v194, 16, v195
	v_and_b32_e32 v195, 0xffff0000, v195
	v_pk_fma_f32 v[8:9], v[8:9], v[154:155], v[192:193]
	v_pk_fma_f32 v[6:7], v[6:7], v[152:153], v[164:165]
	v_pk_fma_f32 v[4:5], v[4:5], v[150:151], v[194:195]
	v_pk_fma_f32 v[2:3], v[2:3], v[148:149], v[166:167]
	v_cvt_pk_bf16_f32 v6, v6, v7
	v_cvt_pk_bf16_f32 v7, v8, v9
	v_cvt_pk_bf16_f32 v8, v2, v3
	v_cvt_pk_bf16_f32 v9, v4, v5
	global_store_dwordx4 v168, v[6:9], s[98:99] offset:256
	s_and_b64 vcc, exec, s[8:9]
	s_mov_b64 s[4:5], -1
	s_cbranch_vccnz .LBB0_400

; __device__ __forceinline__ unsigned pk2(float lo, float hi) { const f32x2_t v = {lo, hi}; const bf16v2_t b = __builtin_convertvector(v, bf16v2_t); return __builtin_bit_cast(unsigned, b); }
; __device__ __forceinline__ float bflo(unsigned u) { return __uint_as_float(u << 16); }
; __device__ __forceinline__ float bfhi(unsigned u) { return __uint_as_float(u & 0xffff0000u); }
; __device__ __forceinline__ void norm_phase(const Args& A, Frame& F, int l, int s, bool latonly, bool tailsum) {
;     ...
;         const int b = row / TB, p = row - b * TB, mr = p < CTXL ? 8 : b;
;         if (latonly && p < CTXL) continue;
;         f32x4 v[4]; float ss = 0.f;
; #pragma unroll
;         for (int j = 0; j < 4; ++j) { const u32x2 xv = cx[j]; v[j][0] = bflo(xv.x); v[j][1] = bfhi(xv.x); v[j][2] = bflo(xv.y); v[j][3] = bfhi(xv.y); }
;         if (tailsum && row >= 16384) {
; #pragma unroll
;             for (int sp = 0; sp < 8; ++sp) {
;                 const u32x2* pr = (const u32x2*)(WSB(WS_PART) + ((size_t)sp * 2048 + (row - 16384)) * D) + F.lane;
; #pragma unroll
;                 for (int j = 0; j < 4; ++j) { const u32x2 pv = pr[64 * j]; v[j][0] += bflo(pv.x); v[j][1] += bfhi(pv.x); v[j][2] += bflo(pv.y); v[j][3] += bfhi(pv.y); }
;             }
;             u32x2* xw = (u32x2*)(WSB(WS_R) + (size_t)row * D) + F.lane;
; #pragma unroll
;             for (int j = 0; j < 4; ++j) { u32x2 o; o.x = pk2(v[j][0], v[j][1]); o.y = pk2(v[j][2], v[j][3]); xw[64 * j] = o; v[j][0] = bflo(o.x); v[j][1] = bfhi(o.x); v[j][2] = bflo(o.y); v[j][3] = bfhi(o.y); }
;         }
; #pragma unroll
;         for (int j = 0; j < 4; ++j) ss += (v[j][0] * v[j][0] + v[j][1] * v[j][1]) + (v[j][2] * v[j][2] + v[j][3] * v[j][3]);
;         const float rstd = rsqrtf(wave_sum(ss) * (1.f / D) + EPS);
;         const float* mp = WSF(WS_MODS) + (size_t)(l * 9 + mr) * NMOD + (size_t)(3 * s) * D;
;         u32x2* o8 = (u32x2*)(WSB(WS_AN) + (size_t)row * D) + F.lane;
; #pragma unroll
;         for (int j = 0; j < 4; ++j) {
;             const int col = 4 * (F.lane + 64 * j);
;             const f32x4 gv = gvh[j], sh = *(const f32x4*)(mp + col), sc = *(const f32x4*)(mp + D + col);
;             const f32x4 y = (v[j] * rstd * gv) * (sc + 1.f) + sh;
;             u32x2 o; o.x = pk2(y[0], y[1]); o.y = pk2(y[2], y[3]);
;             o8[64 * j] = o;
;         }
.LBB0_693:
	s_and_b64 s[40:41], s[40:41], exec
	s_cselect_b32 s4, 8, s4
	s_add_i32 s4, s4, s29
	s_mul_hi_i32 s5, s4, 0x9000
	s_mul_i32 s4, s4, 0x9000
	s_add_u32 s4, s2, s4
	s_addc_u32 s5, s20, s5
	s_add_u32 s40, s4, 0x1000
	s_addc_u32 s41, s5, 0
	global_load_dwordx4 v[192:195], v0, s[40:41]
	global_load_dwordx4 v[196:199], v0, s[4:5]
	global_load_dwordx4 v[200:203], v103, s[40:41]
	global_load_dwordx4 v[204:207], v0, s[4:5] offset:1024
	global_load_dwordx4 v[208:211], v112, s[40:41]
	global_load_dwordx4 v[212:215], v0, s[4:5] offset:2048
	global_load_dwordx4 v[216:219], v113, s[40:41]
	global_load_dwordx4 v[220:223], v0, s[4:5] offset:3072
	v_pk_mul_f32 v[56:57], v[40:41], v[40:41]
	v_pk_mul_f32 v[58:59], v[42:43], v[42:43]
	v_pk_mul_f32 v[60:61], v[44:45], v[44:45]
	v_pk_mul_f32 v[62:63], v[46:47], v[46:47]
	v_cmp_lt_i32_e32 vcc, v176, v175
	v_pk_mov_b32 v[68:69], v[62:63], v[60:61] op_sel:[1,0]
	v_mov_b32_e32 v63, v61
	v_pk_mov_b32 v[60:61], v[58:59], v[56:57] op_sel:[1,0]
	v_mov_b32_e32 v59, v57
	v_mul_f32_e32 v64, v38, v38
	v_mul_f32_e32 v66, v36, v36
	v_cndmask_b32_e32 v67, v174, v176, vcc
	v_pk_add_f32 v[62:63], v[68:69], v[62:63]
	v_pk_add_f32 v[58:59], v[60:61], v[58:59]
	v_pk_fma_f32 v[56:57], v[38:39], v[38:39], v[64:65] op_sel_hi:[1,1,0]
	v_pk_fma_f32 v[64:65], v[36:37], v[36:37], v[66:67] op_sel_hi:[1,1,0]
	v_pk_add_f32 v[60:61], v[62:63], v[62:63] op_sel_hi:[0,1]
	v_pk_add_f32 v[58:59], v[58:59], v[58:59] op_sel_hi:[0,1]
	v_mul_f32_e32 v56, v34, v34
	v_mul_f32_e32 v64, v35, v35
	v_mul_f32_e32 v60, v32, v32
	v_mul_f32_e32 v58, v33, v33
	v_pk_add_f32 v[56:57], v[56:57], v[64:65]
	v_pk_add_f32 v[58:59], v[60:61], v[58:59]
	v_lshlrev_b32_e32 v66, 2, v67
	v_pk_add_f32 v[56:57], v[56:57], v[58:59]
	v_cmp_lt_i32_e32 vcc, v177, v175
	v_add_f32_e32 v56, v56, v57
	ds_bpermute_b32 v57, v66, v56
	v_cndmask_b32_e32 v58, v174, v177, vcc
	v_lshlrev_b32_e32 v58, 2, v58
	v_cmp_lt_i32_e32 vcc, v178, v175
	s_waitcnt lgkmcnt(0)
	v_add_f32_e32 v56, v56, v57
	ds_bpermute_b32 v57, v58, v56
	v_cndmask_b32_e32 v58, v174, v178, vcc
	v_lshlrev_b32_e32 v58, 2, v58
	v_cmp_lt_i32_e32 vcc, v179, v175
	s_waitcnt lgkmcnt(0)
	v_add_f32_e32 v56, v56, v57
	ds_bpermute_b32 v57, v58, v56
	v_cndmask_b32_e32 v58, v174, v179, vcc
	v_lshlrev_b32_e32 v58, 2, v58
	v_cmp_lt_i32_e32 vcc, v180, v175
	s_waitcnt lgkmcnt(0)
	v_add_f32_e32 v56, v56, v57
	ds_bpermute_b32 v57, v58, v56
	v_cndmask_b32_e32 v58, v174, v180, vcc
	v_lshlrev_b32_e32 v58, 2, v58
	v_cmp_lt_i32_e32 vcc, v181, v175
	s_waitcnt lgkmcnt(0)
	v_add_f32_e32 v56, v56, v57
	ds_bpermute_b32 v57, v58, v56
	v_cndmask_b32_e32 v58, v174, v181, vcc
	v_lshlrev_b32_e32 v58, 2, v58
	s_waitcnt lgkmcnt(0)
	v_add_f32_e32 v56, v56, v57
	ds_bpermute_b32 v57, v58, v56
	s_waitcnt lgkmcnt(0)
	v_add_f32_e32 v56, v56, v57
	v_fmamk_f32 v56, v56, 0x3a800000, v170
	v_mul_f32_e32 v57, 0x4b800000, v56
	v_cmp_gt_f32_e32 vcc, s33, v56
	v_pk_mul_f32 v[58:59], v[2:3], v[2:3]
	v_pk_mul_f32 v[60:61], v[4:5], v[4:5]
	v_cndmask_b32_e32 v56, v56, v57, vcc
	v_rsq_f32_e32 v56, v56
	s_nop 0
	v_mul_f32_e32 v57, 0x45800000, v56
	v_cndmask_b32_e32 v56, v56, v57, vcc
	v_pk_mul_f32 v[44:45], v[44:45], v[56:57] op_sel_hi:[1,0]
	v_pk_mul_f32 v[46:47], v[46:47], v[56:57] op_sel_hi:[1,0]
	v_pk_mul_f32 v[44:45], v[4:5], v[44:45]
	v_pk_mul_f32 v[46:47], v[2:3], v[46:47]
	v_pk_mul_f32 v[40:41], v[40:41], v[56:57] op_sel_hi:[1,0]
	v_pk_mul_f32 v[42:43], v[42:43], v[56:57] op_sel_hi:[1,0]
	v_pk_mul_f32 v[40:41], v[8:9], v[40:41]
	v_pk_mul_f32 v[42:43], v[6:7], v[42:43]
	v_pk_mul_f32 v[36:37], v[36:37], v[56:57] op_sel_hi:[1,0]
	v_pk_mul_f32 v[38:39], v[38:39], v[56:57] op_sel_hi:[1,0]
	v_pk_mul_f32 v[36:37], v[12:13], v[36:37]
	v_pk_mul_f32 v[38:39], v[10:11], v[38:39]
	v_pk_mul_f32 v[32:33], v[32:33], v[56:57] op_sel_hi:[1,0]
	v_pk_mul_f32 v[34:35], v[34:35], v[56:57] op_sel_hi:[1,0]
	v_pk_mul_f32 v[32:33], v[16:17], v[32:33]
	v_pk_mul_f32 v[34:35], v[14:15], v[34:35]
	s_waitcnt vmcnt(0)
	v_pk_add_f32 v[194:195], v[194:195], 1.0 op_sel_hi:[1,0]
	v_pk_add_f32 v[192:193], v[192:193], 1.0 op_sel_hi:[1,0]
	v_pk_fma_f32 v[44:45], v[194:195], v[44:45], v[198:199]
	v_pk_fma_f32 v[46:47], v[192:193], v[46:47], v[196:197]
	s_nop 0
	v_cvt_pk_bf16_f32 v46, v46, v47
	v_cvt_pk_bf16_f32 v47, v44, v45
	global_store_dwordx2 v[22:23], v[46:47], off offset:-1024
	v_pk_add_f32 v[202:203], v[202:203], 1.0 op_sel_hi:[1,0]
	v_pk_add_f32 v[200:201], v[200:201], 1.0 op_sel_hi:[1,0]
	v_pk_fma_f32 v[40:41], v[202:203], v[40:41], v[206:207]
	v_pk_fma_f32 v[42:43], v[200:201], v[42:43], v[204:205]
	s_nop 0
	v_cvt_pk_bf16_f32 v42, v42, v43
	v_cvt_pk_bf16_f32 v43, v40, v41
	global_store_dwordx2 v[22:23], v[42:43], off offset:-512
	v_pk_add_f32 v[210:211], v[210:211], 1.0 op_sel_hi:[1,0]
	v_pk_add_f32 v[208:209], v[208:209], 1.0 op_sel_hi:[1,0]
	v_pk_fma_f32 v[36:37], v[210:211], v[36:37], v[214:215]
	v_pk_fma_f32 v[38:39], v[208:209], v[38:39], v[212:213]
	s_nop 0
	v_cvt_pk_bf16_f32 v38, v38, v39
	v_cvt_pk_bf16_f32 v39, v36, v37
	global_store_dwordx2 v[22:23], v[38:39], off
	v_pk_add_f32 v[218:219], v[218:219], 1.0 op_sel_hi:[1,0]
	v_pk_add_f32 v[216:217], v[216:217], 1.0 op_sel_hi:[1,0]
	v_pk_fma_f32 v[32:33], v[218:219], v[32:33], v[222:223]
	v_pk_fma_f32 v[34:35], v[216:217], v[34:35], v[220:221]
	s_nop 0
	v_cvt_pk_bf16_f32 v34, v34, v35
	v_cvt_pk_bf16_f32 v35, v32, v33
	global_store_dwordx2 v[22:23], v[34:35], off offset:512
	v_lshl_add_u64 v[22:23], v[22:23], 0, s[10:11]
	s_and_b64 vcc, exec, s[14:15]
	s_mov_b32 s48, s7
	v_mov_b32_e32 v38, v30
	v_mov_b32_e32 v39, v31
	v_mov_b32_e32 v36, v28
	v_mov_b32_e32 v37, v29
	v_mov_b32_e32 v34, v26
	v_mov_b32_e32 v35, v27
	v_mov_b32_e32 v32, v24
	v_mov_b32_e32 v33, v25
	s_cbranch_vccnz .LBB0_698
	s_branch .LBB0_695
